# stack: peel + saddr K-loop DMA addressing + retention stats DPP + counted P4 waits + leading-half ALIGN barrier moved to the epilogue's first vmcnt(0)
# speedup vs baseline: 1.0117x; 1.0117x over previous
; #define LAS __attribute__((address_space(3)))
; #define LBAR() do { asm volatile("s_waitcnt lgkmcnt(0)" ::: "memory"); __builtin_amdgcn_s_barrier(); asm volatile("" ::: "memory"); } while (0)
; __device__ __forceinline__ unsigned pk2(float lo, float hi) { return pg8::cvt_pk_bf16(lo, hi); }
; __device__ __forceinline__ void retention_unit(LAS unsigned char* lds, const Ptrs& P, int b, int h, int tid) {
;     ...
;             *(LAS v4u*)(Qs + lrow * S72 + lseg * 8) = rq; *(LAS v4u*)(Ks + lrow * S72 + lseg * 8) = rk;
;             v4u k2;
; #pragma unroll
;             for (int t = 0; t < 4; ++t) k2[t] = pk2(bflo(rk[t]) * dkey, bfhi(rk[t]) * dkey);
;             *(LAS v4u*)(K2s + lrow * S72 + lseg * 8) = k2;
;             *(LAS v4u*)(Vs + vrow0 * S144 + vseg * 8) = rv0; *(LAS v4u*)(Vs + (vrow0 + 32) * S144 + vseg * 8) = rv1;
;         }
;         if (n >= 1) {
; #pragma unroll
;             for (int it = 0; it < 4; ++it) sgr[it] = __builtin_nontemporal_load((const v2u*)(gsl + ((size_t)(n - 1) * 64 + 16 * it) * 512));
;         }
;         LBAR();
;         if (n + 1 < 32) { const size_t o4 = (size_t)(n + 1) * 64;
;             rq = __builtin_nontemporal_load((const v4u*)(gq + o4 * 256)); rk = __builtin_nontemporal_load((const v4u*)(gk + o4 * 256)); rv0 = __builtin_nontemporal_load((const v4u*)(gv + o4 * 512)); rv1 = __builtin_nontemporal_load((const v4u*)(gv + (o4 + 32) * 512)); }
;         if (n >= 1) {
;             const int row = tid >> 3, sub = tid & 7;
;             const f32x4 pa = *(const LAS f32x4*)(part + (row * 32 + sub * 4) * 2), pb = *(const LAS f32x4*)(part + (row * 32 + sub * 4) * 2 + 4);
;             float s1 = (pa[0] + pa[2]) + (pb[0] + pb[2]), s2 = (pa[1] + pa[3]) + (pb[1] + pb[3]);
; #pragma unroll
;             for (int x = 1; x < 8; x <<= 1) { s1 += __shfl_xor(s1, x); s2 += __shfl_xor(s2, x); }
;             if (sub == 0) { const float mean = s1 * (1.f / 128.f); float var = s2 * (1.f / 128.f) - mean * mean; var = var < 0.f ? 0.f : var;
;                 stat[row * 2] = mean; stat[row * 2 + 1] = __builtin_amdgcn_rsqf(var + 1e-5f); }
.LBB0_658:
	s_add_i32 s89, s89, 1
	s_bitcmp1_b32 s89, 0
	s_cselect_b32 s18, 0xb400, 0
	s_add_i32 s90, s18, 0
	v_add3_u32 v52, s90, v163, v72
	s_waitcnt vmcnt(7)
	ds_write_b128 v52, v[36:39]
	s_waitcnt vmcnt(6)
	ds_write_b128 v52, v[24:27] offset:9216
	v_lshlrev_b32_e32 v36, 16, v24
	v_and_b32_e32 v37, 0xffff0000, v24
	v_pk_mul_f32 v[36:37], v[102:103], v[36:37]
	v_add_u32_e32 v56, 0, v159
	v_cvt_pk_bf16_f32 v24, v36, v37
	v_lshlrev_b32_e32 v36, 16, v25
	v_and_b32_e32 v37, 0xffff0000, v25
	v_pk_mul_f32 v[36:37], v[102:103], v[36:37]
	v_add_u32_e32 v139, 0x1d400, v56
	v_cvt_pk_bf16_f32 v25, v36, v37
	v_lshlrev_b32_e32 v36, 16, v26
	v_and_b32_e32 v37, 0xffff0000, v26
	v_pk_mul_f32 v[36:37], v[102:103], v[36:37]
	v_and_b32_e32 v60, 64, v131
	v_cvt_pk_bf16_f32 v26, v36, v37
	v_lshlrev_b32_e32 v36, 16, v27
	v_and_b32_e32 v37, 0xffff0000, v27
	v_pk_mul_f32 v[36:37], v[102:103], v[36:37]
	v_add_u32_e32 v60, 64, v60
	v_cvt_pk_bf16_f32 v27, v36, v37
	ds_write_b128 v52, v[24:27] offset:18432
	v_add3_u32 v24, s90, v158, v84
	s_waitcnt vmcnt(5)
	ds_write_b128 v24, v[28:31] offset:27648
	s_waitcnt vmcnt(4)
	ds_write_b128 v24, v[32:35] offset:36864
	v_lshl_add_u64 v[24:25], s[26:27], 0, v[116:117]
	v_add_co_u32_e32 v26, vcc, s58, v24
	v_xor_b32_e32 v61, 1, v131
	s_nop 0
	v_addc_co_u32_e32 v27, vcc, 0, v25, vcc
	v_add_co_u32_e32 v28, vcc, s59, v24
	s_nop 1
	v_addc_co_u32_e32 v29, vcc, 0, v25, vcc
	v_add_co_u32_e32 v30, vcc, s60, v24
	s_nop 1
	v_addc_co_u32_e32 v31, vcc, 0, v25, vcc
	v_add_co_u32_e32 v24, vcc, s61, v24
	s_nop 1
	v_addc_co_u32_e32 v25, vcc, 0, v25, vcc
	global_load_dwordx2 v[54:55], v[26:27], off nt
	global_load_dwordx2 v[52:53], v[28:29], off nt
	global_load_dwordx2 v[122:123], v[30:31], off nt
	global_load_dwordx2 v[118:119], v[24:25], off nt
	v_lshl_add_u64 v[24:25], s[26:27], 0, v[110:111]
	v_add_co_u32_e32 v26, vcc, s62, v24
	v_lshl_add_u64 v[28:29], s[26:27], 0, v[112:113]
	s_nop 0
	v_addc_co_u32_e32 v27, vcc, 0, v25, vcc
	v_add_co_u32_e32 v24, vcc, s63, v24
	s_waitcnt lgkmcnt(0)
	s_barrier
	s_nop 0
	v_addc_co_u32_e32 v25, vcc, 0, v25, vcc
	v_add_co_u32_e32 v30, vcc, s64, v28
	global_load_dwordx4 v[36:39], v[26:27], off nt
	s_nop 0
	global_load_dwordx4 v[24:27], v[24:25], off nt
	v_addc_co_u32_e32 v31, vcc, 0, v29, vcc
	v_add_co_u32_e32 v32, vcc, s65, v28
	s_nop 1
	v_addc_co_u32_e32 v33, vcc, 0, v29, vcc
	global_load_dwordx4 v[28:31], v[30:31], off nt
	s_nop 0
	global_load_dwordx4 v[32:35], v[32:33], off nt
	ds_read_b128 v[56:59], v139
	ds_read_b128 v[184:187], v139 offset:16
	v_cmp_lt_i32_e32 vcc, v61, v60
	s_waitcnt lgkmcnt(1)
	v_pk_add_f32 v[56:57], v[56:57], v[58:59]
	v_cndmask_b32_e32 v61, v131, v61, vcc
	s_waitcnt lgkmcnt(0)
	v_pk_add_f32 v[58:59], v[184:185], v[186:187]
	v_lshlrev_b32_e32 v138, 2, v61
	v_pk_add_f32 v[56:57], v[56:57], v[58:59]
	s_nop 1
	v_add_f32_dpp v56, v56, v56 quad_perm:[1,0,3,2] row_mask:0xf bank_mask:0xf
	v_add_f32_dpp v57, v57, v57 quad_perm:[1,0,3,2] row_mask:0xf bank_mask:0xf
	v_xor_b32_e32 v61, 2, v131
	v_cmp_lt_i32_e32 vcc, v61, v60
	s_nop 1
	v_cndmask_b32_e32 v61, v131, v61, vcc
	v_lshlrev_b32_e32 v140, 2, v61
	v_add_f32_dpp v56, v56, v56 quad_perm:[2,3,0,1] row_mask:0xf bank_mask:0xf
	v_add_f32_dpp v57, v57, v57 quad_perm:[2,3,0,1] row_mask:0xf bank_mask:0xf
	v_xor_b32_e32 v58, 4, v131
	v_cmp_lt_i32_e32 vcc, v58, v60
	s_nop 1
	v_cndmask_b32_e32 v58, v131, v58, vcc
	v_lshlrev_b32_e32 v141, 2, v58
	v_add_f32_dpp v56, v56, v56 row_half_mirror row_mask:0xf bank_mask:0xf
	v_add_f32_dpp v57, v57, v57 row_half_mirror row_mask:0xf bank_mask:0xf
	s_and_saveexec_b64 s[18:19], s[0:1]
	s_cbranch_execz .LBB0_657
	s_waitcnt lgkmcnt(0)
	v_add_u32_e32 v58, 0, v198
	v_pk_mul_f32 v[56:57], v[56:57], s[6:7] op_sel_hi:[1,0]
	v_add_u32_e32 v58, 0x21400, v58
	v_fma_f32 v57, -v56, v56, v57
	v_cmp_ngt_f32_e32 vcc, 0, v57
	s_nop 1
	v_cndmask_b32_e32 v57, 0, v57, vcc
	v_add_f32_e32 v57, 0x3727c5ac, v57
	v_rsq_f32_e32 v57, v57
	ds_write2_b32 v58, v56, v57 offset1:1
	s_branch .LBB0_657
